# final RMSNorm: gain vector hoisted out of the row loop (no per-chunk load and vmcnt(0) in the loop)
# baseline (speedup 1.0000x reference)
.LBB0_7:
	v_readlane_b32 s0, v254, 17
	s_cmp_eq_u32 s0, 23
	s_mov_b64 s[6:7], -1
	s_cbranch_scc0 .LBB0_20
	v_mov_b32_e32 v0, v163
	v_readlane_b32 s0, v254, 0
	v_mov_b32_e32 v2, v163
	v_readlane_b32 s1, v254, 5
	v_ashrrev_i32_e32 v2, 6, v2
	v_lshl_add_u32 v56, s0, 3, v2
	v_cmp_gt_i32_e32 vcc, s33, v56
	s_and_saveexec_b64 s[6:7], vcc
	s_cbranch_execz .LBB0_19
	v_readlane_b32 s2, v254, 25
	v_cmp_lt_i32_e32 vcc, v207, v206
	v_readlane_b32 s3, v254, 26
	s_load_dwordx4 s[8:11], s[2:3], 0x108
	v_cndmask_b32_e32 v2, v204, v207, vcc
	v_cmp_lt_i32_e32 vcc, v208, v206
	v_lshlrev_b32_e32 v60, 2, v2
	v_lshlrev_b32_e32 v0, 4, v0
	v_cndmask_b32_e32 v2, v204, v208, vcc
	v_cmp_lt_i32_e32 vcc, v209, v206
	v_lshlrev_b32_e32 v61, 2, v2
	s_lshl_b32 s0, s1, 3
	v_cndmask_b32_e32 v2, v204, v209, vcc
	v_cmp_lt_i32_e32 vcc, v220, v206
	v_lshlrev_b32_e32 v62, 2, v2
	v_and_b32_e32 v0, 0x3f0, v0
	v_cndmask_b32_e32 v2, v204, v220, vcc
	v_cmp_lt_i32_e32 vcc, v217, v206
	v_lshlrev_b32_e32 v63, 2, v2
	s_waitcnt lgkmcnt(0)
	v_lshl_add_u64 v[50:51], s[10:11], 0, v[0:1]
	v_cndmask_b32_e32 v2, v204, v217, vcc
	v_cmp_lt_i32_e32 vcc, v212, v206
	v_lshlrev_b32_e32 v64, 2, v2
	v_lshl_add_u64 v[52:53], s[8:9], 0, v[0:1]
	v_cndmask_b32_e32 v2, v204, v212, vcc
	v_lshlrev_b32_e32 v65, 2, v2
	s_lshl_b32 s1, s1, 4
	s_mov_b64 s[8:9], 0
	s_add_i32 s2, s0, s0
	global_load_dwordx4 v[72:75], v[52:53], off
	global_load_dwordx4 v[76:79], v[52:53], off offset:1024
	global_load_dwordx4 v[80:83], v[52:53], off offset:2048
	global_load_dwordx4 v[84:87], v[52:53], off offset:3072
	s_branch .LBB0_11

.LBB0_15:
	s_or_b64 exec, exec, s[10:11]
	s_waitcnt vmcnt(3)
	v_mov_b32_e32 v68, v47
	s_waitcnt vmcnt(2)
	v_mov_b32_e32 v69, v43
	v_mov_b32_e32 v66, v46
	v_mov_b32_e32 v67, v42
	v_pk_mul_f32 v[68:69], v[68:69], v[68:69]
	s_waitcnt vmcnt(1)
	v_mov_b32_e32 v70, v39
	v_pk_fma_f32 v[66:67], v[66:67], v[66:67], v[68:69]
	v_mov_b32_e32 v68, v48
	v_mov_b32_e32 v69, v44
	v_pk_fma_f32 v[66:67], v[68:69], v[68:69], v[66:67]
	v_mov_b32_e32 v68, v49
	v_mov_b32_e32 v69, v45
	s_waitcnt vmcnt(0)
	v_mov_b32_e32 v71, v35
	v_pk_fma_f32 v[66:67], v[68:69], v[68:69], v[66:67]
	v_mov_b32_e32 v68, v38
	v_mov_b32_e32 v69, v34
	v_pk_mul_f32 v[70:71], v[70:71], v[70:71]
	v_add_f32_e32 v0, v66, v67
	v_pk_fma_f32 v[68:69], v[68:69], v[68:69], v[70:71]
	v_mov_b32_e32 v70, v40
	v_mov_b32_e32 v71, v36
	v_pk_fma_f32 v[68:69], v[70:71], v[70:71], v[68:69]
	v_mov_b32_e32 v70, v41
	v_mov_b32_e32 v71, v37
	v_pk_fma_f32 v[68:69], v[70:71], v[70:71], v[68:69]
	s_mov_b32 s3, 0x800000
	v_add_f32_e32 v0, v0, v68
	v_add_f32_e32 v0, v0, v69
	ds_bpermute_b32 v66, v60, v0
	s_waitcnt lgkmcnt(0)
	v_add_f32_e32 v0, v0, v66
	ds_bpermute_b32 v66, v61, v0
	s_waitcnt lgkmcnt(0)
	v_add_f32_e32 v0, v0, v66
	ds_bpermute_b32 v66, v62, v0
	s_waitcnt lgkmcnt(0)
	v_add_f32_e32 v0, v0, v66
	ds_bpermute_b32 v66, v63, v0
	s_waitcnt lgkmcnt(0)
	v_add_f32_e32 v0, v0, v66
	ds_bpermute_b32 v66, v64, v0
	s_waitcnt lgkmcnt(0)
	v_add_f32_e32 v0, v0, v66
	ds_bpermute_b32 v66, v65, v0
	s_waitcnt lgkmcnt(0)
	v_add_f32_e32 v0, v0, v66
	v_fmamk_f32 v0, v0, 0x3a800000, v162
	v_cmp_gt_f32_e32 vcc, s3, v0
	v_mul_f32_e32 v66, 0x4b800000, v0
	s_nop 0
	v_cndmask_b32_e32 v0, v0, v66, vcc
	v_rsq_f32_e32 v0, v0
	s_nop 0
	v_mul_f32_e32 v66, 0x45800000, v0
	v_cndmask_b32_e32 v0, v0, v66, vcc
	v_pk_mul_f32 v[46:47], v[46:47], v[0:1] op_sel_hi:[1,0]
	v_pk_mul_f32 v[48:49], v[48:49], v[0:1] op_sel_hi:[1,0]
	v_cmp_gt_i32_e32 vcc, s33, v54
	s_nop 0
	v_pk_mul_f32 v[48:49], v[74:75], v[48:49]
	v_pk_mul_f32 v[46:47], v[72:73], v[46:47]
	global_store_dwordx4 v[58:59], v[46:49], off
	s_nop 1
	v_pk_mul_f32 v[46:47], v[44:45], v[0:1] op_sel_hi:[1,0]
	v_pk_mul_f32 v[48:49], v[42:43], v[0:1] op_sel_hi:[1,0]
	s_nop 0
	v_pk_mul_f32 v[42:43], v[76:77], v[48:49]
	v_pk_mul_f32 v[44:45], v[78:79], v[46:47]
	global_store_dwordx4 v[58:59], v[42:45], off offset:1024
	s_nop 1
	v_pk_mul_f32 v[42:43], v[40:41], v[0:1] op_sel_hi:[1,0]
	v_pk_mul_f32 v[44:45], v[38:39], v[0:1] op_sel_hi:[1,0]
	s_nop 0
	v_pk_mul_f32 v[38:39], v[80:81], v[44:45]
	v_pk_mul_f32 v[40:41], v[82:83], v[42:43]
	global_store_dwordx4 v[58:59], v[38:41], off offset:2048
	s_nop 1
	v_pk_mul_f32 v[38:39], v[36:37], v[0:1] op_sel_hi:[1,0]
	v_pk_mul_f32 v[40:41], v[34:35], v[0:1] op_sel_hi:[1,0]
	s_nop 0
	v_pk_mul_f32 v[34:35], v[84:85], v[40:41]
	v_pk_mul_f32 v[36:37], v[86:87], v[38:39]
	global_store_dwordx4 v[58:59], v[34:37], off offset:3072
	s_and_saveexec_b64 s[10:11], vcc
	s_cbranch_execz .LBB0_17
	v_mov_b32_e32 v40, v27
	v_mov_b32_e32 v41, v31
	v_mov_b32_e32 v38, v26
	v_mov_b32_e32 v39, v30
	v_mov_b32_e32 v48, v19
	v_mov_b32_e32 v49, v23
	v_pk_mul_f32 v[40:41], v[40:41], v[40:41]
	v_mov_b32_e32 v42, v28
	v_mov_b32_e32 v43, v32
	v_mov_b32_e32 v46, v18
	v_mov_b32_e32 v47, v22
	v_pk_mul_f32 v[48:49], v[48:49], v[48:49]
	v_pk_fma_f32 v[38:39], v[38:39], v[38:39], v[40:41]
	v_mov_b32_e32 v44, v29
	v_mov_b32_e32 v45, v33
	v_mov_b32_e32 v58, v20
	v_mov_b32_e32 v59, v24
	v_pk_fma_f32 v[40:41], v[46:47], v[46:47], v[48:49]
	v_pk_fma_f32 v[38:39], v[42:43], v[42:43], v[38:39]
	v_mov_b32_e32 v66, v21
	v_mov_b32_e32 v67, v25
	v_pk_fma_f32 v[40:41], v[58:59], v[58:59], v[40:41]
	v_pk_fma_f32 v[38:39], v[44:45], v[44:45], v[38:39]
	v_pk_fma_f32 v[40:41], v[66:67], v[66:67], v[40:41]
	v_add_f32_e32 v0, v38, v39
	v_add_f32_e32 v0, v41, v0
	v_add_f32_e32 v0, v40, v0
	ds_bpermute_b32 v38, v60, v0
	s_waitcnt lgkmcnt(0)
	v_add_f32_e32 v0, v0, v38
	ds_bpermute_b32 v38, v61, v0
	s_waitcnt lgkmcnt(0)
	v_add_f32_e32 v0, v0, v38
	ds_bpermute_b32 v38, v62, v0
	s_waitcnt lgkmcnt(0)
	v_add_f32_e32 v0, v0, v38
	ds_bpermute_b32 v38, v63, v0
	s_waitcnt lgkmcnt(0)
	v_add_f32_e32 v0, v0, v38
	ds_bpermute_b32 v38, v64, v0
	s_waitcnt lgkmcnt(0)
	v_add_f32_e32 v0, v0, v38
	ds_bpermute_b32 v38, v65, v0
	s_waitcnt lgkmcnt(0)
	v_add_f32_e32 v0, v0, v38
	v_fmamk_f32 v0, v0, 0x3a800000, v162
	v_mul_f32_e32 v38, 0x4b800000, v0
	v_cmp_gt_f32_e32 vcc, s3, v0
	s_nop 1
	v_cndmask_b32_e32 v0, v0, v38, vcc
	v_rsq_f32_e32 v0, v0
	v_lshlrev_b64 v[38:39], 12, v[54:55]
	v_lshl_add_u64 v[38:39], v[50:51], 0, v[38:39]
	v_mul_f32_e32 v40, 0x45800000, v0
	v_cndmask_b32_e32 v0, v0, v40, vcc
	v_pk_mul_f32 v[40:41], v[30:31], v[0:1] op_sel_hi:[1,0]
	v_pk_mul_f32 v[42:43], v[32:33], v[0:1] op_sel_hi:[1,0]
	s_nop 0
	v_pk_mul_f32 v[34:35], v[72:73], v[40:41]
	v_pk_mul_f32 v[36:37], v[74:75], v[42:43]
	global_store_dwordx4 v[38:39], v[34:37], off
	v_pk_mul_f32 v[40:41], v[28:29], v[0:1] op_sel_hi:[1,0]
	v_pk_mul_f32 v[42:43], v[26:27], v[0:1] op_sel_hi:[1,0]
	s_nop 0
	v_pk_mul_f32 v[36:37], v[78:79], v[40:41]
	v_pk_mul_f32 v[34:35], v[76:77], v[42:43]
	global_store_dwordx4 v[38:39], v[34:37], off offset:1024
	v_pk_mul_f32 v[40:41], v[24:25], v[0:1] op_sel_hi:[1,0]
	v_pk_mul_f32 v[42:43], v[22:23], v[0:1] op_sel_hi:[1,0]
	s_nop 0
	v_pk_mul_f32 v[36:37], v[82:83], v[40:41]
	v_pk_mul_f32 v[34:35], v[80:81], v[42:43]
	global_store_dwordx4 v[38:39], v[34:37], off offset:2048
	v_pk_mul_f32 v[40:41], v[20:21], v[0:1] op_sel_hi:[1,0]
	v_pk_mul_f32 v[42:43], v[18:19], v[0:1] op_sel_hi:[1,0]
	s_nop 0
	v_pk_mul_f32 v[36:37], v[86:87], v[40:41]
	v_pk_mul_f32 v[34:35], v[84:85], v[42:43]
	global_store_dwordx4 v[38:39], v[34:37], off offset:3072
.LBB0_17:
	s_or_b64 exec, exec, s[10:11]
	v_cmp_gt_i32_e32 vcc, s33, v56
	s_and_saveexec_b64 s[10:11], vcc
	s_cbranch_execz .LBB0_10
	v_mov_b32_e32 v40, v11
	v_mov_b32_e32 v41, v15
	v_mov_b32_e32 v38, v10
	v_mov_b32_e32 v39, v14
	v_mov_b32_e32 v48, v3
	v_mov_b32_e32 v49, v7
	v_pk_mul_f32 v[40:41], v[40:41], v[40:41]
	v_mov_b32_e32 v42, v12
	v_mov_b32_e32 v43, v16
	v_mov_b32_e32 v46, v2
	v_mov_b32_e32 v47, v6
	v_pk_mul_f32 v[48:49], v[48:49], v[48:49]
	v_pk_fma_f32 v[38:39], v[38:39], v[38:39], v[40:41]
	v_mov_b32_e32 v44, v13
	v_mov_b32_e32 v45, v17
	v_mov_b32_e32 v58, v4
	v_mov_b32_e32 v59, v8
	v_pk_fma_f32 v[40:41], v[46:47], v[46:47], v[48:49]
	v_pk_fma_f32 v[38:39], v[42:43], v[42:43], v[38:39]
	v_mov_b32_e32 v66, v5
	v_mov_b32_e32 v67, v9
	v_pk_fma_f32 v[40:41], v[58:59], v[58:59], v[40:41]
	v_pk_fma_f32 v[38:39], v[44:45], v[44:45], v[38:39]
	v_pk_fma_f32 v[40:41], v[66:67], v[66:67], v[40:41]
	v_add_f32_e32 v0, v38, v39
	v_add_f32_e32 v0, v41, v0
	v_add_f32_e32 v0, v40, v0
	ds_bpermute_b32 v38, v60, v0
	s_waitcnt lgkmcnt(0)
	v_add_f32_e32 v0, v0, v38
	ds_bpermute_b32 v38, v61, v0
	s_waitcnt lgkmcnt(0)
	v_add_f32_e32 v0, v0, v38
	ds_bpermute_b32 v38, v62, v0
	s_waitcnt lgkmcnt(0)
	v_add_f32_e32 v0, v0, v38
	ds_bpermute_b32 v38, v63, v0
	s_waitcnt lgkmcnt(0)
	v_add_f32_e32 v0, v0, v38
	ds_bpermute_b32 v38, v64, v0
	s_waitcnt lgkmcnt(0)
	v_add_f32_e32 v0, v0, v38
	ds_bpermute_b32 v38, v65, v0
	s_waitcnt lgkmcnt(0)
	v_add_f32_e32 v0, v0, v38
	v_fmamk_f32 v0, v0, 0x3a800000, v162
	v_mul_f32_e32 v38, 0x4b800000, v0
	v_cmp_gt_f32_e32 vcc, s3, v0
	s_nop 1
	v_cndmask_b32_e32 v0, v0, v38, vcc
	v_rsq_f32_e32 v0, v0
	v_lshlrev_b64 v[38:39], 12, v[56:57]
	v_lshl_add_u64 v[38:39], v[50:51], 0, v[38:39]
	v_mul_f32_e32 v40, 0x45800000, v0
	v_cndmask_b32_e32 v0, v0, v40, vcc
	v_pk_mul_f32 v[40:41], v[14:15], v[0:1] op_sel_hi:[1,0]
	v_pk_mul_f32 v[42:43], v[16:17], v[0:1] op_sel_hi:[1,0]
	s_nop 0
	v_pk_mul_f32 v[34:35], v[72:73], v[40:41]
	v_pk_mul_f32 v[36:37], v[74:75], v[42:43]
	global_store_dwordx4 v[38:39], v[34:37], off
	v_pk_mul_f32 v[40:41], v[12:13], v[0:1] op_sel_hi:[1,0]
	v_pk_mul_f32 v[42:43], v[10:11], v[0:1] op_sel_hi:[1,0]
	s_nop 0
	v_pk_mul_f32 v[36:37], v[78:79], v[40:41]
	v_pk_mul_f32 v[34:35], v[76:77], v[42:43]
	global_store_dwordx4 v[38:39], v[34:37], off offset:1024
	v_pk_mul_f32 v[40:41], v[8:9], v[0:1] op_sel_hi:[1,0]
	v_pk_mul_f32 v[42:43], v[6:7], v[0:1] op_sel_hi:[1,0]
	s_nop 0
	v_pk_mul_f32 v[36:37], v[82:83], v[40:41]
	v_pk_mul_f32 v[34:35], v[80:81], v[42:43]
	global_store_dwordx4 v[38:39], v[34:37], off offset:2048
	v_pk_mul_f32 v[40:41], v[4:5], v[0:1] op_sel_hi:[1,0]
	v_pk_mul_f32 v[42:43], v[2:3], v[0:1] op_sel_hi:[1,0]
	s_nop 0
	v_pk_mul_f32 v[36:37], v[86:87], v[40:41]
	v_pk_mul_f32 v[34:35], v[84:85], v[42:43]
	global_store_dwordx4 v[38:39], v[34:37], off offset:3072
	s_branch .LBB0_10
